# qup rotary epilogue: eight serialized rope loads per block become four 16-byte loads with one wait; 16 two-byte stores become four 8-byte stores
# baseline (speedup 1.0000x reference)
; DI void phase_qup(const Prm& p, unsigned char* smem_raw, int l, int S, int& base) {
;     ...
;     auto epi = [&](f32x16 (&acc)[2], int wm, int wn, int lane) __attribute__((always_inline)) {
;       const int lr = lane & 31, lh = lane >> 5;
;       const int tokl = wn * 32 + lr, tok = m0 + tokl;
;       const float sc = st[tokl] * QS;
; #pragma unroll
;       for (int i = 0; i < 2; ++i) {
;         const int nb = n0 + wm * 64 + i * 32;
;         const int head = nb / 96, within = nb - head * 96;
;         const f32x16& a = acc[i];
;         if (within < 64) {
; #pragma unroll
;           for (int h2 = 0; h2 < 2; ++h2) {
;             u32x4 o;
; #pragma unroll
;             for (int e = 0; e < 4; ++e) o[e] = pack2(a[8 * h2 + 2 * e] * sc, a[8 * h2 + 2 * e + 1] * sc);
;             *(u32x4*)(p.qc + (size_t)tok * 384 + nb + 16 * lh + 8 * h2) = o;
;           }
;         } else {
;           const int pos = tok & (S - 1);
; #pragma unroll
;           for (int q = 0; q < 2; ++q)
; #pragma unroll
;             for (int e = 0; e < 4; ++e) {
;               const int r = 4 * q + e, ii = 8 * q + 4 * lh + e;
;               const float2 cs = p.rope[pos * 16 + ii];
;               const float x1 = a[r] * sc, x2 = a[r + 8] * sc;
;               p.qc[(size_t)tok * 384 + head * 96 + 64 + ii] = f2bf(x1 * cs.x - x2 * cs.y);
;               p.qc[(size_t)tok * 384 + head * 96 + 80 + ii] = f2bf(x1 * cs.y + x2 * cs.x);
;             }
.LBB0_2050:
	v_lshl_or_b32 v0, v79, 2, v239
	ds_read_b32 v0, v0
	s_waitcnt vmcnt(3)
	v_add_u32_e32 v34, s55, v75
	v_or_b32_e32 v35, s54, v79
	v_mad_i64_i32 v[36:37], s[2:3], v35, s33, 0
	s_waitcnt vmcnt(2) lgkmcnt(0)
	v_mul_f32_e32 v38, 0x3e16c740, v0
	v_mul_hi_i32 v0, v34, s82
	v_lshrrev_b32_e32 v39, 31, v0
	v_lshrrev_b32_e32 v0, 4, v0
	v_add_u32_e32 v0, v0, v39
	v_mul_lo_u32 v0, v0, s86
	v_readlane_b32 s2, v254, 45
	v_readlane_b32 s36, v253, 24
	s_waitcnt vmcnt(0)
	v_lshlrev_b32_e32 v48, 2, v77
	v_sub_u32_e32 v0, v34, v0
	v_and_b32_e32 v35, s2, v35
	v_readlane_b32 s50, v253, 38
	v_readlane_b32 s51, v253, 39
	v_cmp_lt_i32_e32 vcc, 63, v0
	v_mul_f32_e32 v47, v18, v38
	v_lshl_add_u64 v[36:37], s[50:51], 0, v[36:37]
	v_mul_f32_e32 v45, v26, v38
	v_lshlrev_b32_e32 v18, 1, v48
	v_mul_f32_e32 v46, v19, v38
	v_mul_f32_e32 v43, v27, v38
	v_mul_f32_e32 v44, v20, v38
	v_mul_f32_e32 v41, v28, v38
	v_mul_f32_e32 v42, v21, v38
	v_mul_f32_e32 v39, v29, v38
	v_mul_f32_e32 v40, v22, v38
	v_mul_f32_e32 v28, v30, v38
	v_mul_f32_e32 v29, v23, v38
	v_mul_f32_e32 v26, v31, v38
	v_mul_f32_e32 v27, v24, v38
	v_mul_f32_e32 v23, v32, v38
	v_mul_f32_e32 v24, v25, v38
	v_mul_f32_e32 v22, v33, v38
	v_lshl_or_b32 v20, v35, 4, v48
	v_readlane_b32 s37, v253, 25
	v_readlane_b32 s38, v253, 26
	v_readlane_b32 s39, v253, 27
	v_readlane_b32 s40, v253, 28
	v_readlane_b32 s41, v253, 29
	v_readlane_b32 s42, v253, 30
	v_readlane_b32 s43, v253, 31
	v_readlane_b32 s44, v253, 32
	v_readlane_b32 s45, v253, 33
	v_readlane_b32 s46, v253, 34
	v_readlane_b32 s47, v253, 35
	v_readlane_b32 s48, v253, 36
	v_readlane_b32 s49, v253, 37
	s_and_saveexec_b64 s[2:3], vcc
	s_xor_b64 s[2:3], exec, s[2:3]
	s_cbranch_execz .LBB0_2052
	v_readlane_b32 s36, v253, 8
	v_mov_b32_e32 v21, v1
	v_readlane_b32 s40, v253, 12
	v_readlane_b32 s41, v253, 13
	v_sub_u32_e32 v48, v34, v0
	v_ashrrev_i32_e32 v49, 31, v48
	v_lshl_add_u64 v[30:31], v[20:21], 3, s[40:41]
	global_load_dwordx4 v[50:53], v[30:31], off
	global_load_dwordx4 v[54:57], v[30:31], off offset:16
	global_load_dwordx4 v[58:61], v[30:31], off offset:64
	global_load_dwordx4 v[62:65], v[30:31], off offset:80
	v_mov_b32_e32 v19, v1
	v_lshl_add_u64 v[48:49], v[48:49], 1, v[36:37]
	v_lshl_add_u64 v[48:49], v[48:49], 0, v[18:19]
	v_readlane_b32 s37, v253, 9
	v_readlane_b32 s38, v253, 10
	v_readlane_b32 s39, v253, 11
	v_readlane_b32 s42, v253, 14
	v_readlane_b32 s43, v253, 15
	v_readlane_b32 s44, v253, 16
	v_readlane_b32 s45, v253, 17
	v_readlane_b32 s46, v253, 18
	v_readlane_b32 s47, v253, 19
	v_readlane_b32 s48, v253, 20
	v_readlane_b32 s49, v253, 21
	v_readlane_b32 s50, v253, 22
	v_readlane_b32 s51, v253, 23
	s_waitcnt vmcnt(0)
	v_mul_f32_e32 v0, v45, v51
	v_mul_f32_e32 v51, v47, v51
	v_fmac_f32_e32 v51, v45, v50
	v_fma_f32 v50, v47, v50, -v0
	v_mul_f32_e32 v0, v43, v53
	v_mul_f32_e32 v53, v46, v53
	v_fmac_f32_e32 v53, v43, v52
	v_fma_f32 v52, v46, v52, -v0
	v_mul_f32_e32 v0, v41, v55
	v_mul_f32_e32 v55, v44, v55
	v_fmac_f32_e32 v55, v41, v54
	v_fma_f32 v54, v44, v54, -v0
	v_mul_f32_e32 v0, v39, v57
	v_mul_f32_e32 v57, v42, v57
	v_fmac_f32_e32 v57, v39, v56
	v_fma_f32 v56, v42, v56, -v0
	v_mul_f32_e32 v0, v28, v59
	v_mul_f32_e32 v59, v40, v59
	v_fmac_f32_e32 v59, v28, v58
	v_fma_f32 v58, v40, v58, -v0
	v_mul_f32_e32 v0, v26, v61
	v_mul_f32_e32 v61, v29, v61
	v_fmac_f32_e32 v61, v26, v60
	v_fma_f32 v60, v29, v60, -v0
	v_mul_f32_e32 v0, v23, v63
	v_mul_f32_e32 v63, v27, v63
	v_fmac_f32_e32 v63, v23, v62
	v_fma_f32 v62, v27, v62, -v0
	v_mul_f32_e32 v0, v22, v65
	v_mul_f32_e32 v65, v24, v65
	v_fmac_f32_e32 v65, v22, v64
	v_fma_f32 v64, v24, v64, -v0
	v_cvt_pk_bf16_f32 v0, v50, v52
	v_cvt_pk_bf16_f32 v50, v51, v53
	v_cvt_pk_bf16_f32 v51, v55, v57
	v_cvt_pk_bf16_f32 v53, v54, v56
	v_mov_b32_e32 v52, v0
	global_store_dwordx2 v[48:49], v[52:53], off offset:128
	global_store_dwordx2 v[48:49], v[50:51], off offset:160
	v_cvt_pk_bf16_f32 v0, v58, v60
	v_cvt_pk_bf16_f32 v58, v59, v61
	v_cvt_pk_bf16_f32 v59, v63, v65
	v_cvt_pk_bf16_f32 v61, v62, v64
	v_mov_b32_e32 v60, v0
	global_store_dwordx2 v[48:49], v[60:61], off offset:144
	global_store_dwordx2 v[48:49], v[58:59], off offset:176

; DI void phase_qup(const Prm& p, unsigned char* smem_raw, int l, int S, int& base) {
;     ...
;       for (int i = 0; i < 2; ++i) {
;         const int nb = n0 + wm * 64 + i * 32;
;         const int head = nb / 96, within = nb - head * 96;
;         const f32x16& a = acc[i];
;         if (within < 64) {
; #pragma unroll
;           for (int h2 = 0; h2 < 2; ++h2) {
;             u32x4 o;
; #pragma unroll
;             for (int e = 0; e < 4; ++e) o[e] = pack2(a[8 * h2 + 2 * e] * sc, a[8 * h2 + 2 * e + 1] * sc);
;             *(u32x4*)(p.qc + (size_t)tok * 384 + nb + 16 * lh + 8 * h2) = o;
;           }
;         } else {
;           const int pos = tok & (S - 1);
; #pragma unroll
;           for (int q = 0; q < 2; ++q)
; #pragma unroll
;             for (int e = 0; e < 4; ++e) {
;               const int r = 4 * q + e, ii = 8 * q + 4 * lh + e;
;               const float2 cs = p.rope[pos * 16 + ii];
;               const float x1 = a[r] * sc, x2 = a[r + 8] * sc;
;               p.qc[(size_t)tok * 384 + head * 96 + 64 + ii] = f2bf(x1 * cs.x - x2 * cs.y);
;               p.qc[(size_t)tok * 384 + head * 96 + 80 + ii] = f2bf(x1 * cs.y + x2 * cs.x);
;             }
.LBB0_2054:
	s_or_b64 exec, exec, s[2:3]
	v_add3_u32 v19, s55, v75, 32
	v_mul_hi_i32 v21, v19, s82
	v_lshrrev_b32_e32 v22, 31, v21
	v_lshrrev_b32_e32 v21, 4, v21
	v_add_u32_e32 v21, v21, v22
	v_mul_lo_u32 v21, v21, s86
	v_sub_u32_e32 v19, v19, v21
	v_cmp_lt_i32_e32 vcc, 63, v19
	v_mul_f32_e32 v28, v2, v38
	v_mul_f32_e32 v27, v10, v38
	v_mul_f32_e32 v26, v3, v38
	v_mul_f32_e32 v25, v11, v38
	v_mul_f32_e32 v24, v4, v38
	v_mul_f32_e32 v23, v12, v38
	v_mul_f32_e32 v22, v5, v38
	v_mul_f32_e32 v12, v13, v38
	v_mul_f32_e32 v11, v6, v38
	v_mul_f32_e32 v10, v14, v38
	v_mul_f32_e32 v7, v7, v38
	v_mul_f32_e32 v6, v15, v38
	v_mul_f32_e32 v5, v8, v38
	v_mul_f32_e32 v4, v16, v38
	v_mul_f32_e32 v3, v9, v38
	v_mul_f32_e32 v2, v17, v38
	s_and_saveexec_b64 s[2:3], vcc
	s_xor_b64 s[2:3], exec, s[2:3]
	s_cbranch_execz .LBB0_2056
	v_readlane_b32 s36, v253, 8
	v_mov_b32_e32 v21, v1
	v_readlane_b32 s40, v253, 12
	v_readlane_b32 s41, v253, 13
	v_ashrrev_i32_e32 v0, 31, v19
	v_sub_co_u32_e32 v8, vcc, v34, v19
	v_lshl_add_u64 v[14:15], v[20:21], 3, s[40:41]
	global_load_dwordx4 v[50:53], v[14:15], off
	global_load_dwordx4 v[54:57], v[14:15], off offset:16
	global_load_dwordx4 v[58:61], v[14:15], off offset:64
	global_load_dwordx4 v[62:65], v[14:15], off offset:80
	v_subb_co_u32_e32 v9, vcc, v35, v0, vcc
	v_lshl_add_u64 v[8:9], v[8:9], 1, v[36:37]
	v_mov_b32_e32 v19, v1
	v_lshl_add_u64 v[8:9], v[8:9], 0, v[18:19]
	v_readlane_b32 s37, v253, 9
	v_readlane_b32 s38, v253, 10
	v_readlane_b32 s39, v253, 11
	v_readlane_b32 s42, v253, 14
	v_readlane_b32 s43, v253, 15
	v_readlane_b32 s44, v253, 16
	v_readlane_b32 s45, v253, 17
	v_readlane_b32 s46, v253, 18
	v_readlane_b32 s47, v253, 19
	v_readlane_b32 s48, v253, 20
	v_readlane_b32 s49, v253, 21
	v_readlane_b32 s50, v253, 22
	v_readlane_b32 s51, v253, 23
	s_waitcnt vmcnt(0)
	v_mul_f32_e32 v0, v27, v51
	v_mul_f32_e32 v51, v28, v51
	v_fmac_f32_e32 v51, v27, v50
	v_fma_f32 v50, v28, v50, -v0
	v_mul_f32_e32 v0, v25, v53
	v_mul_f32_e32 v53, v26, v53
	v_fmac_f32_e32 v53, v25, v52
	v_fma_f32 v52, v26, v52, -v0
	v_mul_f32_e32 v0, v23, v55
	v_mul_f32_e32 v55, v24, v55
	v_fmac_f32_e32 v55, v23, v54
	v_fma_f32 v54, v24, v54, -v0
	v_mul_f32_e32 v0, v12, v57
	v_mul_f32_e32 v57, v22, v57
	v_fmac_f32_e32 v57, v12, v56
	v_fma_f32 v56, v22, v56, -v0
	v_mul_f32_e32 v0, v10, v59
	v_mul_f32_e32 v59, v11, v59
	v_fmac_f32_e32 v59, v10, v58
	v_fma_f32 v58, v11, v58, -v0
	v_mul_f32_e32 v0, v6, v61
	v_mul_f32_e32 v61, v7, v61
	v_fmac_f32_e32 v61, v6, v60
	v_fma_f32 v60, v7, v60, -v0
	v_mul_f32_e32 v0, v4, v63
	v_mul_f32_e32 v63, v5, v63
	v_fmac_f32_e32 v63, v4, v62
	v_fma_f32 v62, v5, v62, -v0
	v_mul_f32_e32 v0, v2, v65
	v_mul_f32_e32 v65, v3, v65
	v_fmac_f32_e32 v65, v2, v64
	v_fma_f32 v64, v3, v64, -v0
	v_cvt_pk_bf16_f32 v0, v50, v52
	v_cvt_pk_bf16_f32 v50, v51, v53
	v_cvt_pk_bf16_f32 v51, v55, v57
	v_cvt_pk_bf16_f32 v53, v54, v56
	v_mov_b32_e32 v52, v0
	global_store_dwordx2 v[8:9], v[52:53], off offset:192
	global_store_dwordx2 v[8:9], v[50:51], off offset:224
	v_cvt_pk_bf16_f32 v0, v58, v60
	v_cvt_pk_bf16_f32 v58, v59, v61
	v_cvt_pk_bf16_f32 v59, v63, v65
	v_cvt_pk_bf16_f32 v61, v62, v64
	v_mov_b32_e32 v60, v0
	global_store_dwordx2 v[8:9], v[60:61], off offset:208
	global_store_dwordx2 v[8:9], v[58:59], off offset:240
